# grid barrier body rewritten: generation in LDS (no integer divisions), invalidate at arrival, top-level last arriver bumps every XCC generation word directly (one flag hop less)
# speedup vs baseline: 1.0843x; 1.0078x over previous
; DEV unsigned xb_ld(unsigned* p) { return __hip_atomic_load(p, __ATOMIC_RELAXED, __HIP_MEMORY_SCOPE_AGENT); }
; DEV unsigned xb_add(unsigned* p, unsigned v) { return __hip_atomic_fetch_add(p, v, __ATOMIC_RELAXED, __HIP_MEMORY_SCOPE_AGENT); }
; #define XB_SPIN(cond, bar) do { unsigned _sp = 0; while (cond) { __builtin_amdgcn_s_sleep(1); \
;     if ((++_sp & 255u) == 0u) { if (xb_ld(&(bar)[XB_TMO])) break; if (_sp > XB_SPIN_CAP) { atomicAdd(&(bar)[XB_TMO], 1u); break; } } } } while (0)
; DEV void xcd_barrier(const XcdBarrier& b) {
;     ...
;         unsigned nloc = b.st[0], nx = b.st[1];
;         if (nloc == 0u) { xcd_barrier_complete(bar, b.x, nloc, nx); b.st[0] = nloc; b.st[1] = nx; }
;         const unsigned old = xb_add(&bar[XB_XSUB(b.x)], 1u);
;         const unsigned gen = old / nloc;
;         if (old + 1u == (gen + 1u) * nloc) {
;             __builtin_amdgcn_fence(__ATOMIC_RELEASE, "agent");
;             asm volatile("s_waitcnt vmcnt(0)" ::: "memory");
;             const unsigned og = xb_add(&bar[XB_TOP], 1u);
;             const unsigned tg = og / nx;
;             if (og + 1u == (tg + 1u) * nx) xb_add(&bar[XB_TOPGEN], 1u);
;             else XB_SPIN(xb_ld(&bar[XB_TOPGEN]) == tg, bar);
;             __builtin_amdgcn_fence(__ATOMIC_ACQUIRE, "agent");
;             xb_add(&bar[XB_XGEN(b.x)], 1u);
;             asm volatile("s_waitcnt vmcnt(0)" ::: "memory");
;         } else {
;             XB_SPIN(xb_ld(&bar[XB_XGEN(b.x)]) == gen, bar);
;             __builtin_amdgcn_fence(__ATOMIC_ACQUIRE, "agent");
;             asm volatile("s_waitcnt vmcnt(0)" ::: "memory");
;         }
.LBB0_134:
	s_lshl_b32 s6, s3, 8
	v_mov_b32_e32 v2, 0x20008
	s_add_u32 s6, s28, s6
	s_addc_u32 s7, s29, 0
	ds_read_b32 v2, v2
	v_mov_b32_e32 v4, 0x1000
	v_mov_b32_e32 v5, 1
	global_atomic_add v4, v4, v5, s[6:7] offset:1024 sc0
	s_waitcnt vmcnt(0) lgkmcnt(0)
	buffer_inv sc1
	v_readfirstlane_b32 s8, v4
	v_readfirstlane_b32 s9, v3
	v_readfirstlane_b32 s10, v2
	v_readfirstlane_b32 s11, v1
	s_add_i32 s12, s10, 1
	v_mov_b32_e32 v6, 0x20008
	v_mov_b32_e32 v5, s12
	ds_write_b32 v6, v5
	s_add_i32 s8, s8, 1
	s_mul_i32 s13, s12, s9
	s_cmp_lg_u32 s8, s13
	s_cbranch_scc1 .Lxb0_poll
	buffer_wbl2 sc1
	s_waitcnt vmcnt(0)
	v_mov_b32_e32 v4, 0x3000
	v_mov_b32_e32 v5, 1
	global_atomic_add v4, v4, v5, s[28:29] offset:1024 sc0
	s_waitcnt vmcnt(0)
	v_readfirstlane_b32 s8, v4
	s_mul_i32 s13, s12, s11
	s_add_i32 s8, s8, 1
	s_cmp_lg_u32 s8, s13
	s_cbranch_scc1 .Lxb0_poll
	v_mov_b32_e32 v4, 0x2000
	v_mov_b32_e32 v6, 0x3000
	global_atomic_add v4, v5, s[28:29] offset:1024
	global_atomic_add v4, v5, s[28:29] offset:1280
	global_atomic_add v4, v5, s[28:29] offset:1536
	global_atomic_add v4, v5, s[28:29] offset:1792
	global_atomic_add v4, v5, s[28:29] offset:2048
	global_atomic_add v4, v5, s[28:29] offset:2304
	global_atomic_add v4, v5, s[28:29] offset:2560
	global_atomic_add v4, v5, s[28:29] offset:2816
	global_atomic_add v4, v5, s[28:29] offset:3072
	global_atomic_add v4, v5, s[28:29] offset:3328
	global_atomic_add v4, v5, s[28:29] offset:3584
	global_atomic_add v4, v5, s[28:29] offset:3840
	global_atomic_add v6, v5, s[28:29] offset:0
	global_atomic_add v6, v5, s[28:29] offset:256
	global_atomic_add v6, v5, s[28:29] offset:512
	global_atomic_add v6, v5, s[28:29] offset:768
	s_branch .Lxb0_done
.Lxb0_poll:
	v_mov_b32_e32 v4, 0x2000
	s_mov_b32 s8, 0
.Lxb0_spin:
	global_load_dword v5, v4, s[6:7] offset:1024 sc1
	s_add_u32 s8, s8, 1
	s_waitcnt vmcnt(0)
	v_readfirstlane_b32 s13, v5
	s_cmp_lg_u32 s13, s10
	s_cbranch_scc1 .Lxb0_done
	s_sleep 1
	s_cmp_lt_u32 s8, 0x40000
	s_cbranch_scc1 .Lxb0_spin
	v_mov_b32_e32 v4, 0
	v_mov_b32_e32 v5, 1
	global_atomic_add v4, v5, s[28:29] offset:512
.Lxb0_done:
	s_waitcnt lgkmcnt(0)
